# c11_pv_group0_under_maxtree
# baseline (speedup 1.0000x reference)
.LBB0_871:
	s_add_i32 s80, s75, -3
	s_lshl_b32 s76, s74, 14
	s_add_i32 s8, s69, s76
	v_lshl_add_u64 v[2:3], v[226:227], 0, s[34:35]
	s_mov_b32 m0, s8
	s_nop 0
	global_load_lds_dwordx4 v[2:3], off
	s_add_i32 m0, s8, 0x2000
	s_mul_i32 s8, s60, 0x6300
	s_add_i32 s61, s68, s8
	global_load_lds_dwordx4 v[226:227], off
	s_add_i32 m0, s61, 0xc000
	s_add_i32 s8, s75, -1
	s_cmp_lt_u32 s8, s77
	s_cselect_b32 s8, s8, s73
	s_lshl_b32 s8, s8, 6
	s_lshl_b64 s[58:59], s[8:9], 12
	v_lshl_add_u64 v[2:3], v[218:219], 0, s[58:59]
	global_load_lds_dwordx4 v[2:3], off
	v_lshl_add_u64 v[2:3], v[2:3], 0, s[12:13]
	s_add_i32 m0, s61, 0xe100
	s_lshl_b64 s[82:83], s[8:9], 7
	global_load_lds_dwordx4 v[2:3], off
	v_lshl_add_u64 v[2:3], v[224:225], 0, s[82:83]
	s_add_i32 m0, s61, 0x10200
	s_nop 0
	global_load_lds_dwordx4 v[2:3], off
	s_mul_i32 s8, s79, 0x6300
	s_add_i32 s8, s8, 0
	v_add_u32_e32 v0, s8, v237
	ds_read_b128 v[2:5], v0 offset:49152
	ds_read_b128 v[6:9], v0 offset:50176
	s_waitcnt lgkmcnt(0)
	v_mfma_f32_32x32x16_bf16 v[112:127], v[2:5], v[188:191], 0
	v_mfma_f32_32x32x16_bf16 v[128:143], v[6:9], v[188:191], 0
	ds_read_b128 v[2:5], v0 offset:51264
	ds_read_b128 v[6:9], v0 offset:52288
	s_waitcnt lgkmcnt(0)
	v_mfma_f32_32x32x16_bf16 v[112:127], v[2:5], v[184:187], v[112:127]
	v_mfma_f32_32x32x16_bf16 v[128:143], v[6:9], v[184:187], v[128:143]
	ds_read_b128 v[2:5], v0 offset:53376
	ds_read_b128 v[6:9], v0 offset:54400
	s_waitcnt lgkmcnt(0)
	v_mfma_f32_32x32x16_bf16 v[112:127], v[2:5], v[180:183], v[112:127]
	v_mfma_f32_32x32x16_bf16 v[128:143], v[6:9], v[180:183], v[128:143]
	ds_read_b128 v[2:5], v0 offset:55488
	ds_read_b128 v[6:9], v0 offset:56512
	s_waitcnt lgkmcnt(0)
	v_mfma_f32_32x32x16_bf16 v[112:127], v[2:5], v[176:179], v[112:127]
	v_mfma_f32_32x32x16_bf16 v[128:143], v[6:9], v[176:179], v[128:143]
	ds_read_b128 v[2:5], v0 offset:57600
	ds_read_b128 v[6:9], v0 offset:58624
	s_waitcnt lgkmcnt(0)
	v_mfma_f32_32x32x16_bf16 v[112:127], v[2:5], v[172:175], v[112:127]
	v_mfma_f32_32x32x16_bf16 v[128:143], v[6:9], v[172:175], v[128:143]
	ds_read_b128 v[2:5], v0 offset:59712
	ds_read_b128 v[6:9], v0 offset:60736
	s_waitcnt lgkmcnt(0)
	v_mfma_f32_32x32x16_bf16 v[112:127], v[2:5], v[168:171], v[112:127]
	v_mfma_f32_32x32x16_bf16 v[128:143], v[6:9], v[168:171], v[128:143]
	ds_read_b128 v[2:5], v0 offset:61824
	ds_read_b128 v[6:9], v0 offset:62848
	s_waitcnt lgkmcnt(0)
	v_mfma_f32_32x32x16_bf16 v[112:127], v[2:5], v[164:167], v[112:127]
	v_mfma_f32_32x32x16_bf16 v[128:143], v[6:9], v[164:167], v[128:143]
	ds_read_b128 v[2:5], v0 offset:63936
	ds_read_b128 v[6:9], v0 offset:64960
	v_add_u32_e32 v0, 0xc000, v0
	s_waitcnt lgkmcnt(0)
	v_mfma_f32_32x32x16_bf16 v[112:127], v[2:5], v[160:163], v[112:127]
	ds_read_b128 v[2:5], v0 offset:17920
	ds_read_b128 v[10:13], v0 offset:16896
	v_mfma_f32_32x32x16_bf16 v[128:143], v[6:9], v[160:163], v[128:143]
	ds_read_b128 v[6:9], v0 offset:20032
	ds_read_b128 v[192:195], v0 offset:19008
	ds_read_b128 v[196:199], v0 offset:22144
	ds_read_b128 v[200:203], v0 offset:21120
	ds_read_b128 v[204:207], v0 offset:24256
	ds_read_b128 v[208:211], v0 offset:23232
	v_add_f32_e32 v0, 0, v96
	v_add_f32_e32 v0, v97, v0
	v_add_f32_e32 v0, v98, v0
	v_add_f32_e32 v0, v99, v0
	v_add_f32_e32 v0, v100, v0
	v_add_f32_e32 v0, v101, v0
	s_waitcnt lgkmcnt(0)
	v_mfma_f32_32x32x16_bf16 v[112:127], v[10:13], v[156:159], v[112:127]
	v_add_f32_e32 v0, v102, v0
	v_add_f32_e32 v0, v103, v0
	v_add_f32_e32 v0, v104, v0
	v_add_f32_e32 v0, v105, v0
	v_add_f32_e32 v0, v106, v0
	v_add_f32_e32 v0, v107, v0
	v_add_f32_e32 v0, v108, v0
	v_mfma_f32_32x32x16_bf16 v[128:143], v[2:5], v[156:159], v[128:143]
	v_add_f32_e32 v0, v109, v0
	v_add_f32_e32 v0, v110, v0
	v_add_f32_e32 v0, v111, v0
	v_add_f32_e32 v0, v80, v0
	v_add_f32_e32 v0, v81, v0
	v_add_f32_e32 v0, v82, v0
	v_add_f32_e32 v0, v83, v0
	v_mfma_f32_32x32x16_bf16 v[112:127], v[192:195], v[152:155], v[112:127]
	v_add_f32_e32 v0, v84, v0
	v_add_f32_e32 v0, v85, v0
	v_add_f32_e32 v0, v86, v0
	v_add_f32_e32 v0, v87, v0
	v_add_f32_e32 v0, v88, v0
	v_add_f32_e32 v0, v89, v0
	v_add_f32_e32 v0, v90, v0
	v_mfma_f32_32x32x16_bf16 v[128:143], v[6:9], v[152:155], v[128:143]
	v_add_f32_e32 v0, v91, v0
	v_add_f32_e32 v0, v92, v0
	v_add_f32_e32 v0, v93, v0
	v_add_f32_e32 v0, v94, v0
	v_add_f32_e32 v14, v95, v0
	v_mov_b32_e32 v15, v14
	s_nop 1
	v_permlane32_swap_b32_e32 v14, v15
	v_mfma_f32_32x32x16_bf16 v[112:127], v[200:203], v[148:151], v[112:127]
	v_cvt_pk_bf16_f32 v192, v96, v97
	v_cvt_pk_bf16_f32 v193, v98, v99
	v_cvt_pk_bf16_f32 v194, v100, v101
	v_cvt_pk_bf16_f32 v195, v102, v103
	v_cvt_pk_bf16_f32 v10, v104, v105
	v_cvt_pk_bf16_f32 v11, v106, v107
	v_cvt_pk_bf16_f32 v12, v108, v109
	v_mfma_f32_32x32x16_bf16 v[128:143], v[196:199], v[148:151], v[128:143]
	v_cvt_pk_bf16_f32 v13, v110, v111
	v_cvt_pk_bf16_f32 v6, v80, v81
	v_cvt_pk_bf16_f32 v7, v82, v83
	v_cvt_pk_bf16_f32 v8, v84, v85
	v_cvt_pk_bf16_f32 v9, v86, v87
	v_cvt_pk_bf16_f32 v2, v88, v89
	v_cvt_pk_bf16_f32 v3, v90, v91
	v_mfma_f32_32x32x16_bf16 v[112:127], v[208:211], v[144:147], v[112:127]
	v_cvt_pk_bf16_f32 v4, v92, v93
	v_cvt_pk_bf16_f32 v5, v94, v95
	v_mfma_f32_32x32x16_bf16 v[128:143], v[204:207], v[144:147], v[128:143]
	s_cmp_gt_i32 s80, s72
	s_cbranch_scc1 .Lold_mla_odd
	v_lshl_add_u32 v0, s60, 14, v235
	ds_read_b64_tr_b16 v[208:209], v0 offset:0
	ds_read_b64_tr_b16 v[210:211], v0 offset:0x800
	ds_read_b64_tr_b16 v[204:205], v0 offset:0x1000
	ds_read_b64_tr_b16 v[206:207], v0 offset:0x1800
	ds_read_b64_tr_b16 v[200:201], v0 offset:0x2000
	ds_read_b64_tr_b16 v[202:203], v0 offset:0x2800
	ds_read_b64_tr_b16 v[196:197], v0 offset:0x3000
	ds_read_b64_tr_b16 v[198:199], v0 offset:0x3800
	s_nop 1
	v_max3_f32 v245, v112, v113, v114
	v_max3_f32 v246, v128, v129, v130
	v_max3_f32 v245, v245, v115, v116
	v_max3_f32 v246, v246, v131, v132
	v_max3_f32 v245, v245, v117, v118
	v_max3_f32 v246, v246, v133, v134
	v_max3_f32 v245, v245, v119, v120
	v_max3_f32 v246, v246, v135, v136
	v_max3_f32 v245, v245, v121, v122
	v_max3_f32 v246, v246, v137, v138
	s_waitcnt lgkmcnt(0)
	v_mfma_f32_32x32x16_bf16 v[64:79], v[192:195], v[208:211], v[64:79]
	v_max3_f32 v245, v245, v123, v124
	v_max3_f32 v246, v246, v139, v140
	v_max3_f32 v245, v245, v125, v126
	v_max3_f32 v246, v246, v141, v142
	v_max_f32_e32 v245, v245, v127
	v_max_f32_e32 v246, v246, v143
	v_mfma_f32_32x32x16_bf16 v[64:79], v[10:13], v[204:207], v[64:79]
	v_max_f32_e32 v245, v245, v246
	v_mov_b32_e32 v246, v245
	v_mfma_f32_32x32x16_bf16 v[64:79], v[6:9], v[200:203], v[64:79]
	s_nop 0
	v_permlane32_swap_b32_e32 v245, v246
	v_max_f32_e32 v245, v245, v246
	v_mfma_f32_32x32x16_bf16 v[64:79], v[2:5], v[196:199], v[64:79]
	v_sub_f32_e32 v246, v245, v236
	v_cmp_ge_f32_e32 vcc, s29, v246
	s_cmp_eq_u64 vcc, exec
	v_mov_b32_e32 v240, 1.0
	s_cbranch_scc0 .Lfm_odd_ev
.Lfm_odd_exp:
	v_sub_f32_e32 v96, v112, v236
	v_sub_f32_e32 v97, v113, v236
	ds_read_b64_tr_b16 v[112:113], v0 offset:0x200
	v_sub_f32_e32 v98, v114, v236
	v_sub_f32_e32 v99, v115, v236
	ds_read_b64_tr_b16 v[114:115], v0 offset:0xa00
	v_exp_f32_e32 v96, v96
	v_exp_f32_e32 v97, v97
	v_sub_f32_e32 v100, v116, v236
	v_sub_f32_e32 v101, v117, v236
	ds_read_b64_tr_b16 v[116:117], v0 offset:0x1200
	v_exp_f32_e32 v98, v98
	v_exp_f32_e32 v99, v99
	v_sub_f32_e32 v102, v118, v236
	v_sub_f32_e32 v103, v119, v236
	ds_read_b64_tr_b16 v[118:119], v0 offset:0x1a00
	v_exp_f32_e32 v100, v100
	v_exp_f32_e32 v101, v101
	v_sub_f32_e32 v104, v120, v236
	v_sub_f32_e32 v105, v121, v236
	ds_read_b64_tr_b16 v[120:121], v0 offset:0x2200
	v_exp_f32_e32 v102, v102
	v_exp_f32_e32 v103, v103
	v_sub_f32_e32 v106, v122, v236
	v_sub_f32_e32 v107, v123, v236
	ds_read_b64_tr_b16 v[122:123], v0 offset:0x2a00
	v_exp_f32_e32 v104, v104
	v_exp_f32_e32 v105, v105
	v_sub_f32_e32 v108, v124, v236
	v_sub_f32_e32 v109, v125, v236
	ds_read_b64_tr_b16 v[124:125], v0 offset:0x3200
	v_exp_f32_e32 v106, v106
	v_exp_f32_e32 v107, v107
	v_sub_f32_e32 v110, v126, v236
	v_sub_f32_e32 v111, v127, v236
	ds_read_b64_tr_b16 v[126:127], v0 offset:0x3a00
	v_exp_f32_e32 v108, v108
	v_exp_f32_e32 v109, v109
	v_exp_f32_e32 v110, v110
	v_exp_f32_e32 v111, v111
	ds_read_b64_tr_b16 v[208:209], v0 offset:0x400
	ds_read_b64_tr_b16 v[210:211], v0 offset:0xc00
	ds_read_b64_tr_b16 v[204:205], v0 offset:0x1400
	ds_read_b64_tr_b16 v[206:207], v0 offset:0x1c00
	ds_read_b64_tr_b16 v[200:201], v0 offset:0x2400
	ds_read_b64_tr_b16 v[202:203], v0 offset:0x2c00
	ds_read_b64_tr_b16 v[196:197], v0 offset:0x3400
	ds_read_b64_tr_b16 v[198:199], v0 offset:0x3c00
	s_waitcnt lgkmcnt(8)
	v_mfma_f32_32x32x16_bf16 v[48:63], v[192:195], v[112:115], v[48:63]
	v_sub_f32_e32 v80, v128, v236
	v_sub_f32_e32 v81, v129, v236
	v_sub_f32_e32 v82, v130, v236
	v_sub_f32_e32 v83, v131, v236
	v_mfma_f32_32x32x16_bf16 v[48:63], v[10:13], v[116:119], v[48:63]
	v_sub_f32_e32 v84, v132, v236
	v_sub_f32_e32 v85, v133, v236
	v_sub_f32_e32 v86, v134, v236
	v_sub_f32_e32 v87, v135, v236
	v_mfma_f32_32x32x16_bf16 v[48:63], v[6:9], v[120:123], v[48:63]
	v_sub_f32_e32 v88, v136, v236
	v_sub_f32_e32 v89, v137, v236
	v_sub_f32_e32 v90, v138, v236
	v_sub_f32_e32 v91, v139, v236
	v_mfma_f32_32x32x16_bf16 v[48:63], v[2:5], v[124:127], v[48:63]
	v_sub_f32_e32 v92, v140, v236
	v_sub_f32_e32 v93, v141, v236
	v_sub_f32_e32 v94, v142, v236
	v_sub_f32_e32 v95, v143, v236
	ds_read_b64_tr_b16 v[112:113], v0 offset:0x600
	ds_read_b64_tr_b16 v[114:115], v0 offset:0xe00
	ds_read_b64_tr_b16 v[116:117], v0 offset:0x1600
	ds_read_b64_tr_b16 v[118:119], v0 offset:0x1e00
	ds_read_b64_tr_b16 v[120:121], v0 offset:0x2600
	ds_read_b64_tr_b16 v[122:123], v0 offset:0x2e00
	ds_read_b64_tr_b16 v[124:125], v0 offset:0x3600
	ds_read_b64_tr_b16 v[126:127], v0 offset:0x3e00
	s_waitcnt lgkmcnt(8)
	v_mfma_f32_32x32x16_bf16 v[32:47], v[192:195], v[208:211], v[32:47]
	v_exp_f32_e32 v80, v80
	v_exp_f32_e32 v81, v81
	v_mfma_f32_32x32x16_bf16 v[32:47], v[10:13], v[204:207], v[32:47]
	v_exp_f32_e32 v82, v82
	v_exp_f32_e32 v83, v83
	v_mfma_f32_32x32x16_bf16 v[32:47], v[6:9], v[200:203], v[32:47]
	v_exp_f32_e32 v84, v84
	v_exp_f32_e32 v85, v85
	v_mfma_f32_32x32x16_bf16 v[32:47], v[2:5], v[196:199], v[32:47]
	v_exp_f32_e32 v86, v86
	v_exp_f32_e32 v87, v87
	s_waitcnt lgkmcnt(0)
	v_mfma_f32_32x32x16_bf16 v[16:31], v[192:195], v[112:115], v[16:31]
	v_exp_f32_e32 v88, v88
	v_exp_f32_e32 v89, v89
	v_mfma_f32_32x32x16_bf16 v[16:31], v[10:13], v[116:119], v[16:31]
	v_exp_f32_e32 v90, v90
	v_exp_f32_e32 v91, v91
	v_mfma_f32_32x32x16_bf16 v[16:31], v[6:9], v[120:123], v[16:31]
	v_exp_f32_e32 v92, v92
	v_exp_f32_e32 v93, v93
	v_mfma_f32_32x32x16_bf16 v[16:31], v[2:5], v[124:127], v[16:31]
	v_exp_f32_e32 v94, v94
	v_exp_f32_e32 v95, v95
	v_cmp_gt_f32_e32 vcc, 1.0, v240
	s_cbranch_vccnz .Lresc_mla_odd_blk
.LBB0_876:
	s_waitcnt vmcnt(0)
	s_add_i32 s60, s74, 1
	s_cmp_lg_u32 s74, 2
	s_cselect_b32 s81, s60, 0
	s_waitcnt vmcnt(0)
	s_barrier
	s_lshl_b32 s78, s81, 14
	s_add_i32 s60, s69, s78
	v_lshl_add_u64 v[2:3], v[222:223], 0, s[58:59]
	v_lshl_add_u64 v[4:5], v[2:3], 0, s[14:15]
	s_mov_b32 m0, s60
	s_add_i32 s8, s8, s70
	global_load_lds_dwordx4 v[4:5], off
	v_lshl_add_u64 v[2:3], v[2:3], 0, s[16:17]
	s_add_i32 m0, s60, 0x2000
	s_add_i32 s82, s8, s71
	global_load_lds_dwordx4 v[2:3], off
	s_add_i32 m0, s82, 0xc000
	s_cmp_ge_u32 s75, s77
	s_cselect_b64 s[58:59], -1, 0
	s_cmp_lt_u32 s75, s77
	s_cselect_b32 s8, s75, s73
	s_lshl_b32 s8, s8, 6
	s_lshl_b64 s[60:61], s[8:9], 12
	v_lshl_add_u64 v[2:3], v[218:219], 0, s[60:61]
	global_load_lds_dwordx4 v[2:3], off
	v_lshl_add_u64 v[2:3], v[2:3], 0, s[12:13]
	s_add_i32 m0, s82, 0xe100
	s_lshl_b64 s[60:61], s[8:9], 7
	global_load_lds_dwordx4 v[2:3], off
	v_lshl_add_u64 v[2:3], v[224:225], 0, s[60:61]
	s_add_i32 m0, s82, 0x10200
	s_nop 0
	global_load_lds_dwordx4 v[2:3], off
	s_mul_i32 s8, s74, 0x6300
	v_add_u32_e32 v0, s8, v238
	ds_read_b128 v[2:5], v0 offset:49152
	ds_read_b128 v[6:9], v0 offset:50176
	s_waitcnt lgkmcnt(0)
	v_mfma_f32_32x32x16_bf16 v[112:127], v[2:5], v[188:191], 0
	v_mfma_f32_32x32x16_bf16 v[128:143], v[6:9], v[188:191], 0
	ds_read_b128 v[2:5], v0 offset:51264
	ds_read_b128 v[6:9], v0 offset:52288
	s_waitcnt lgkmcnt(0)
	v_mfma_f32_32x32x16_bf16 v[112:127], v[2:5], v[184:187], v[112:127]
	v_mfma_f32_32x32x16_bf16 v[128:143], v[6:9], v[184:187], v[128:143]
	ds_read_b128 v[2:5], v0 offset:53376
	ds_read_b128 v[6:9], v0 offset:54400
	s_waitcnt lgkmcnt(0)
	v_mfma_f32_32x32x16_bf16 v[112:127], v[2:5], v[180:183], v[112:127]
	v_mfma_f32_32x32x16_bf16 v[128:143], v[6:9], v[180:183], v[128:143]
	ds_read_b128 v[2:5], v0 offset:55488
	ds_read_b128 v[6:9], v0 offset:56512
	s_waitcnt lgkmcnt(0)
	v_mfma_f32_32x32x16_bf16 v[112:127], v[2:5], v[176:179], v[112:127]
	v_mfma_f32_32x32x16_bf16 v[128:143], v[6:9], v[176:179], v[128:143]
	ds_read_b128 v[2:5], v0 offset:57600
	ds_read_b128 v[6:9], v0 offset:58624
	s_waitcnt lgkmcnt(0)
	v_mfma_f32_32x32x16_bf16 v[112:127], v[2:5], v[172:175], v[112:127]
	v_mfma_f32_32x32x16_bf16 v[128:143], v[6:9], v[172:175], v[128:143]
	ds_read_b128 v[2:5], v0 offset:59712
	ds_read_b128 v[6:9], v0 offset:60736
	s_waitcnt lgkmcnt(0)
	v_mfma_f32_32x32x16_bf16 v[112:127], v[2:5], v[168:171], v[112:127]
	v_mfma_f32_32x32x16_bf16 v[128:143], v[6:9], v[168:171], v[128:143]
	ds_read_b128 v[2:5], v0 offset:61824
	ds_read_b128 v[6:9], v0 offset:62848
	s_waitcnt lgkmcnt(0)
	v_mfma_f32_32x32x16_bf16 v[112:127], v[2:5], v[164:167], v[112:127]
	v_mfma_f32_32x32x16_bf16 v[128:143], v[6:9], v[164:167], v[128:143]
	ds_read_b128 v[2:5], v0 offset:63936
	ds_read_b128 v[6:9], v0 offset:64960
	v_add_u32_e32 v0, 0xc000, v0
	s_waitcnt lgkmcnt(0)
	v_mfma_f32_32x32x16_bf16 v[112:127], v[2:5], v[160:163], v[112:127]
	ds_read_b128 v[2:5], v0 offset:17920
	ds_read_b128 v[10:13], v0 offset:16896
	v_mfma_f32_32x32x16_bf16 v[128:143], v[6:9], v[160:163], v[128:143]
	ds_read_b128 v[6:9], v0 offset:20032
	ds_read_b128 v[192:195], v0 offset:19008
	ds_read_b128 v[196:199], v0 offset:22144
	ds_read_b128 v[200:203], v0 offset:21120
	ds_read_b128 v[204:207], v0 offset:24256
	ds_read_b128 v[208:211], v0 offset:23232
	v_add_f32_e32 v0, 0, v96
	v_add_f32_e32 v0, v97, v0
	v_add_f32_e32 v0, v98, v0
	v_add_f32_e32 v0, v99, v0
	v_add_f32_e32 v0, v100, v0
	v_add_f32_e32 v0, v101, v0
	s_waitcnt lgkmcnt(0)
	v_mfma_f32_32x32x16_bf16 v[112:127], v[10:13], v[156:159], v[112:127]
	v_add_f32_e32 v0, v102, v0
	v_add_f32_e32 v0, v103, v0
	v_add_f32_e32 v0, v104, v0
	v_add_f32_e32 v0, v105, v0
	v_add_f32_e32 v0, v106, v0
	v_add_f32_e32 v0, v107, v0
	v_add_f32_e32 v0, v108, v0
	v_mfma_f32_32x32x16_bf16 v[128:143], v[2:5], v[156:159], v[128:143]
	v_add_f32_e32 v0, v109, v0
	v_add_f32_e32 v0, v110, v0
	v_add_f32_e32 v0, v111, v0
	v_add_f32_e32 v0, v80, v0
	v_add_f32_e32 v0, v81, v0
	v_add_f32_e32 v0, v82, v0
	v_add_f32_e32 v0, v83, v0
	v_mfma_f32_32x32x16_bf16 v[112:127], v[192:195], v[152:155], v[112:127]
	v_add_f32_e32 v0, v84, v0
	v_add_f32_e32 v0, v85, v0
	v_add_f32_e32 v0, v86, v0
	v_add_f32_e32 v0, v87, v0
	v_add_f32_e32 v0, v88, v0
	v_add_f32_e32 v0, v89, v0
	v_add_f32_e32 v0, v90, v0
	v_mfma_f32_32x32x16_bf16 v[128:143], v[6:9], v[152:155], v[128:143]
	v_add_f32_e32 v0, v91, v0
	v_add_f32_e32 v0, v92, v0
	v_add_f32_e32 v0, v93, v0
	v_add_f32_e32 v0, v94, v0
	v_add_f32_e32 v241, v95, v0
	v_mov_b32_e32 v242, v241
	s_nop 1
	v_permlane32_swap_b32_e32 v241, v242
	v_mfma_f32_32x32x16_bf16 v[112:127], v[200:203], v[148:151], v[112:127]
	v_cvt_pk_bf16_f32 v192, v96, v97
	v_cvt_pk_bf16_f32 v193, v98, v99
	v_cvt_pk_bf16_f32 v194, v100, v101
	v_cvt_pk_bf16_f32 v195, v102, v103
	v_cvt_pk_bf16_f32 v10, v104, v105
	v_cvt_pk_bf16_f32 v11, v106, v107
	v_cvt_pk_bf16_f32 v12, v108, v109
	v_mfma_f32_32x32x16_bf16 v[128:143], v[196:199], v[148:151], v[128:143]
	v_cvt_pk_bf16_f32 v13, v110, v111
	v_cvt_pk_bf16_f32 v6, v80, v81
	v_cvt_pk_bf16_f32 v7, v82, v83
	v_cvt_pk_bf16_f32 v8, v84, v85
	v_cvt_pk_bf16_f32 v9, v86, v87
	v_cvt_pk_bf16_f32 v2, v88, v89
	v_cvt_pk_bf16_f32 v3, v90, v91
	v_mfma_f32_32x32x16_bf16 v[112:127], v[208:211], v[144:147], v[112:127]
	v_cvt_pk_bf16_f32 v4, v92, v93
	v_cvt_pk_bf16_f32 v5, v94, v95
	v_mfma_f32_32x32x16_bf16 v[128:143], v[204:207], v[144:147], v[128:143]
	s_cmp_lt_i32 s80, s72
	s_cbranch_scc0 .Lold_mla_even
	v_lshl_add_u32 v243, s79, 14, v235
	ds_read_b64_tr_b16 v[208:209], v243 offset:0
	ds_read_b64_tr_b16 v[210:211], v243 offset:0x800
	ds_read_b64_tr_b16 v[204:205], v243 offset:0x1000
	ds_read_b64_tr_b16 v[206:207], v243 offset:0x1800
	ds_read_b64_tr_b16 v[200:201], v243 offset:0x2000
	ds_read_b64_tr_b16 v[202:203], v243 offset:0x2800
	ds_read_b64_tr_b16 v[196:197], v243 offset:0x3000
	ds_read_b64_tr_b16 v[198:199], v243 offset:0x3800
	s_nop 1
	v_max3_f32 v245, v112, v113, v114
	v_max3_f32 v246, v128, v129, v130
	v_max3_f32 v245, v245, v115, v116
	v_max3_f32 v246, v246, v131, v132
	v_max3_f32 v245, v245, v117, v118
	v_max3_f32 v246, v246, v133, v134
	v_max3_f32 v245, v245, v119, v120
	v_max3_f32 v246, v246, v135, v136
	v_max3_f32 v245, v245, v121, v122
	v_max3_f32 v246, v246, v137, v138
	s_waitcnt lgkmcnt(0)
	v_mfma_f32_32x32x16_bf16 v[64:79], v[192:195], v[208:211], v[64:79]
	v_max3_f32 v245, v245, v123, v124
	v_max3_f32 v246, v246, v139, v140
	v_max3_f32 v245, v245, v125, v126
	v_max3_f32 v246, v246, v141, v142
	v_max_f32_e32 v245, v245, v127
	v_max_f32_e32 v246, v246, v143
	v_mfma_f32_32x32x16_bf16 v[64:79], v[10:13], v[204:207], v[64:79]
	v_max_f32_e32 v245, v245, v246
	v_mov_b32_e32 v246, v245
	v_mfma_f32_32x32x16_bf16 v[64:79], v[6:9], v[200:203], v[64:79]
	s_nop 0
	v_permlane32_swap_b32_e32 v245, v246
	v_max_f32_e32 v245, v245, v246
	v_mfma_f32_32x32x16_bf16 v[64:79], v[2:5], v[196:199], v[64:79]
	v_sub_f32_e32 v246, v245, v236
	v_cmp_ge_f32_e32 vcc, s29, v246
	s_cmp_eq_u64 vcc, exec
	v_mov_b32_e32 v0, 1.0
	s_cbranch_scc0 .Lfm_even_ev
.Lfm_even_exp:
	v_sub_f32_e32 v96, v112, v236
	v_sub_f32_e32 v97, v113, v236
	ds_read_b64_tr_b16 v[112:113], v243 offset:0x200
	v_sub_f32_e32 v98, v114, v236
	v_sub_f32_e32 v99, v115, v236
	ds_read_b64_tr_b16 v[114:115], v243 offset:0xa00
	v_exp_f32_e32 v96, v96
	v_exp_f32_e32 v97, v97
	v_sub_f32_e32 v100, v116, v236
	v_sub_f32_e32 v101, v117, v236
	ds_read_b64_tr_b16 v[116:117], v243 offset:0x1200
	v_exp_f32_e32 v98, v98
	v_exp_f32_e32 v99, v99
	v_sub_f32_e32 v102, v118, v236
	v_sub_f32_e32 v103, v119, v236
	ds_read_b64_tr_b16 v[118:119], v243 offset:0x1a00
	v_exp_f32_e32 v100, v100
	v_exp_f32_e32 v101, v101
	v_sub_f32_e32 v104, v120, v236
	v_sub_f32_e32 v105, v121, v236
	ds_read_b64_tr_b16 v[120:121], v243 offset:0x2200
	v_exp_f32_e32 v102, v102
	v_exp_f32_e32 v103, v103
	v_sub_f32_e32 v106, v122, v236
	v_sub_f32_e32 v107, v123, v236
	ds_read_b64_tr_b16 v[122:123], v243 offset:0x2a00
	v_exp_f32_e32 v104, v104
	v_exp_f32_e32 v105, v105
	v_sub_f32_e32 v108, v124, v236
	v_sub_f32_e32 v109, v125, v236
	ds_read_b64_tr_b16 v[124:125], v243 offset:0x3200
	v_exp_f32_e32 v106, v106
	v_exp_f32_e32 v107, v107
	v_sub_f32_e32 v110, v126, v236
	v_sub_f32_e32 v111, v127, v236
	ds_read_b64_tr_b16 v[126:127], v243 offset:0x3a00
	v_exp_f32_e32 v108, v108
	v_exp_f32_e32 v109, v109
	v_exp_f32_e32 v110, v110
	v_exp_f32_e32 v111, v111
	ds_read_b64_tr_b16 v[208:209], v243 offset:0x400
	ds_read_b64_tr_b16 v[210:211], v243 offset:0xc00
	ds_read_b64_tr_b16 v[204:205], v243 offset:0x1400
	ds_read_b64_tr_b16 v[206:207], v243 offset:0x1c00
	ds_read_b64_tr_b16 v[200:201], v243 offset:0x2400
	ds_read_b64_tr_b16 v[202:203], v243 offset:0x2c00
	ds_read_b64_tr_b16 v[196:197], v243 offset:0x3400
	ds_read_b64_tr_b16 v[198:199], v243 offset:0x3c00
	s_waitcnt lgkmcnt(8)
	v_mfma_f32_32x32x16_bf16 v[48:63], v[192:195], v[112:115], v[48:63]
	v_sub_f32_e32 v80, v128, v236
	v_sub_f32_e32 v81, v129, v236
	v_sub_f32_e32 v82, v130, v236
	v_sub_f32_e32 v83, v131, v236
	v_mfma_f32_32x32x16_bf16 v[48:63], v[10:13], v[116:119], v[48:63]
	v_sub_f32_e32 v84, v132, v236
	v_sub_f32_e32 v85, v133, v236
	v_sub_f32_e32 v86, v134, v236
	v_sub_f32_e32 v87, v135, v236
	v_mfma_f32_32x32x16_bf16 v[48:63], v[6:9], v[120:123], v[48:63]
	v_sub_f32_e32 v88, v136, v236
	v_sub_f32_e32 v89, v137, v236
	v_sub_f32_e32 v90, v138, v236
	v_sub_f32_e32 v91, v139, v236
	v_mfma_f32_32x32x16_bf16 v[48:63], v[2:5], v[124:127], v[48:63]
	v_sub_f32_e32 v92, v140, v236
	v_sub_f32_e32 v93, v141, v236
	v_sub_f32_e32 v94, v142, v236
	v_sub_f32_e32 v95, v143, v236
	ds_read_b64_tr_b16 v[112:113], v243 offset:0x600
	ds_read_b64_tr_b16 v[114:115], v243 offset:0xe00
	ds_read_b64_tr_b16 v[116:117], v243 offset:0x1600
	ds_read_b64_tr_b16 v[118:119], v243 offset:0x1e00
	ds_read_b64_tr_b16 v[120:121], v243 offset:0x2600
	ds_read_b64_tr_b16 v[122:123], v243 offset:0x2e00
	ds_read_b64_tr_b16 v[124:125], v243 offset:0x3600
	ds_read_b64_tr_b16 v[126:127], v243 offset:0x3e00
	s_waitcnt lgkmcnt(8)
	v_mfma_f32_32x32x16_bf16 v[32:47], v[192:195], v[208:211], v[32:47]
	v_exp_f32_e32 v80, v80
	v_exp_f32_e32 v81, v81
	v_mfma_f32_32x32x16_bf16 v[32:47], v[10:13], v[204:207], v[32:47]
	v_exp_f32_e32 v82, v82
	v_exp_f32_e32 v83, v83
	v_mfma_f32_32x32x16_bf16 v[32:47], v[6:9], v[200:203], v[32:47]
	v_exp_f32_e32 v84, v84
	v_exp_f32_e32 v85, v85
	v_mfma_f32_32x32x16_bf16 v[32:47], v[2:5], v[196:199], v[32:47]
	v_exp_f32_e32 v86, v86
	v_exp_f32_e32 v87, v87
	s_waitcnt lgkmcnt(0)
	v_mfma_f32_32x32x16_bf16 v[16:31], v[192:195], v[112:115], v[16:31]
	v_exp_f32_e32 v88, v88
	v_exp_f32_e32 v89, v89
	v_mfma_f32_32x32x16_bf16 v[16:31], v[10:13], v[116:119], v[16:31]
	v_exp_f32_e32 v90, v90
	v_exp_f32_e32 v91, v91
	v_mfma_f32_32x32x16_bf16 v[16:31], v[6:9], v[120:123], v[16:31]
	v_exp_f32_e32 v92, v92
	v_exp_f32_e32 v93, v93
	v_mfma_f32_32x32x16_bf16 v[16:31], v[2:5], v[124:127], v[16:31]
	v_exp_f32_e32 v94, v94
	v_exp_f32_e32 v95, v95
	v_cmp_gt_f32_e32 vcc, 1.0, v0
	s_cbranch_vccnz .Lresc_mla_even_blk

.LBB0_1422:
	s_lshl_b32 s18, s44, 14
	s_add_i32 s52, s81, s18
	s_mov_b32 m0, s52
	v_lshl_add_u64 v[0:1], v[194:195], 0, s[14:15]
	global_load_lds_dwordx4 v[194:195], off
	s_add_i32 m0, s52, 0x2000
	s_mul_i32 s52, s54, 0x2100
	s_add_i32 s52, s22, s52
	global_load_lds_dwordx4 v[0:1], off
	s_add_i32 m0, s52, 0xc000
	s_add_i32 s52, s45, -1
	s_cmp_lt_u32 s52, s2
	s_cselect_b32 s55, s52, s3
	s_lshl_b32 s56, s55, 6
	v_mad_u64_u32 v[0:1], s[52:53], s56, v209, v[192:193]
	v_lshl_add_u64 v[0:1], v[0:1], 0, s[10:11]
	global_load_lds_dwordx4 v[0:1], off
	s_mul_i32 s52, s55, 0x60000
	s_mul_hi_u32 s53, s56, 0x1800
	s_mul_i32 s55, s69, 0x2100
	s_add_i32 s71, s55, 0
	s_sub_i32 s55, s65, 64
	v_cvt_f32_u32_e32 v0, s55
	v_add_u32_e32 v166, s71, v220
	v_add_u32_e32 v167, s71, v217
	ds_read_b128 v[4:7], v166 offset:49152
	ds_read_b128 v[8:11], v167 offset:49152
	v_sub_f32_e32 v196, v0, v161
	v_fma_f32 v0, v210, v196, -v221
	v_cvt_pk_bf16_f32 v1, v0, v3
	v_lshlrev_b32_e32 v1, 16, v1
	v_sub_f32_e32 v0, v0, v1
	v_cvt_pk_bf16_f32 v2, v0, v3
	v_lshlrev_b32_e32 v2, 16, v2
	v_sub_f32_e32 v0, v0, v2
	v_cvt_pk_bf16_f32 v1, v1, v2
	v_cvt_pk_bf16_f32 v0, v0, v3
	s_nop 0
	v_cndmask_b32_e64 v2, 0, v0, s[4:5]
	v_cndmask_b32_e64 v0, 0, v160, s[4:5]
	v_cndmask_b32_e64 v1, 0, v1, s[4:5]
	s_nop 1
	v_mfma_f32_32x32x16_bf16 v[128:143], v[248:251], v[0:3], 0
	v_mfma_f32_32x32x16_bf16 v[112:127], v[252:255], v[0:3], 0
	v_add_f32_e32 v1, 0, v96
	v_add_f32_e32 v1, v97, v1
	v_add_f32_e32 v1, v98, v1
	v_add_f32_e32 v1, v99, v1
	v_add_f32_e32 v1, v100, v1
	v_add_f32_e32 v1, v101, v1
	v_add_f32_e32 v1, v102, v1
	s_waitcnt lgkmcnt(0)
	v_mfma_f32_32x32x16_bf16 v[128:143], v[8:11], v[156:159], v[128:143]
	v_add_f32_e32 v1, v103, v1
	v_add_f32_e32 v1, v104, v1
	v_add_f32_e32 v1, v105, v1
	v_add_f32_e32 v1, v106, v1
	v_add_f32_e32 v1, v107, v1
	v_add_f32_e32 v1, v108, v1
	v_add_f32_e32 v1, v109, v1
	v_mfma_f32_32x32x16_bf16 v[112:127], v[4:7], v[156:159], v[112:127]
	ds_read_b128 v[4:7], v166 offset:51264
	ds_read_b128 v[8:11], v167 offset:51264
	v_add_f32_e32 v1, v110, v1
	v_add_f32_e32 v1, v111, v1
	v_add_f32_e32 v1, v80, v1
	v_add_f32_e32 v1, v81, v1
	v_add_f32_e32 v1, v82, v1
	v_add_f32_e32 v1, v83, v1
	s_waitcnt lgkmcnt(0)
	v_mfma_f32_32x32x16_bf16 v[128:143], v[8:11], v[152:155], v[128:143]
	v_add_f32_e32 v1, v84, v1
	v_add_f32_e32 v1, v85, v1
	v_add_f32_e32 v1, v86, v1
	v_add_f32_e32 v1, v87, v1
	v_add_f32_e32 v1, v88, v1
	v_add_f32_e32 v1, v89, v1
	v_add_f32_e32 v1, v90, v1
	v_mfma_f32_32x32x16_bf16 v[112:127], v[4:7], v[152:155], v[112:127]
	ds_read_b128 v[4:7], v166 offset:53376
	ds_read_b128 v[8:11], v167 offset:53376
	v_add_f32_e32 v1, v91, v1
	v_add_f32_e32 v1, v92, v1
	v_add_f32_e32 v1, v93, v1
	v_add_f32_e32 v1, v94, v1
	v_add_f32_e32 v223, v95, v1
	v_mov_b32_e32 v224, v223
	s_waitcnt lgkmcnt(0)
	v_mfma_f32_32x32x16_bf16 v[128:143], v[8:11], v[148:151], v[128:143]
	v_permlane32_swap_b32_e32 v223, v224
	v_mfma_f32_32x32x16_bf16 v[112:127], v[4:7], v[148:151], v[112:127]
	ds_read_b128 v[4:7], v166 offset:55488
	ds_read_b128 v[8:11], v167 offset:55488
	v_cvt_pk_bf16_f32 v166, v96, v97
	v_cvt_pk_bf16_f32 v167, v98, v99
	v_cvt_pk_bf16_f32 v168, v100, v101
	v_cvt_pk_bf16_f32 v169, v102, v103
	v_cvt_pk_bf16_f32 v12, v104, v105
	v_cvt_pk_bf16_f32 v13, v106, v107
	s_waitcnt lgkmcnt(0)
	v_mfma_f32_32x32x16_bf16 v[128:143], v[8:11], v[144:147], v[128:143]
	v_cvt_pk_bf16_f32 v14, v108, v109
	v_cvt_pk_bf16_f32 v15, v110, v111
	v_cvt_pk_bf16_f32 v8, v80, v81
	v_cvt_pk_bf16_f32 v9, v82, v83
	v_cvt_pk_bf16_f32 v10, v84, v85
	v_cvt_pk_bf16_f32 v11, v86, v87
	v_mfma_f32_32x32x16_bf16 v[112:127], v[4:7], v[144:147], v[112:127]
	v_cvt_pk_bf16_f32 v4, v88, v89
	v_cvt_pk_bf16_f32 v5, v90, v91
	v_cvt_pk_bf16_f32 v6, v92, v93
	v_cvt_pk_bf16_f32 v7, v94, v95
	v_lshl_add_u32 v1, s54, 14, v215
	ds_read_b64_tr_b16 v[182:183], v1 offset:0
	ds_read_b64_tr_b16 v[184:185], v1 offset:0x800
	ds_read_b64_tr_b16 v[178:179], v1 offset:0x1000
	ds_read_b64_tr_b16 v[180:181], v1 offset:0x1800
	s_add_i32 s70, s45, -3
	s_add_i32 s54, s19, s45
	ds_read_b64_tr_b16 v[174:175], v1 offset:0x2000
	s_cmp_eq_u32 s54, 3
	ds_read_b64_tr_b16 v[176:177], v1 offset:0x2800
	s_cselect_b64 s[54:55], -1, 0
	ds_read_b64_tr_b16 v[170:171], v1 offset:0x3000
	v_cndmask_b32_e64 v2, 0, 1, s[54:55]
	ds_read_b64_tr_b16 v[172:173], v1 offset:0x3800
	s_cmp_lt_i32 s70, s31
	s_cbranch_scc0 .Lold_odd
	v_max3_f32 v245, v128, v129, v130
	v_max3_f32 v246, v112, v113, v114
	v_max3_f32 v245, v245, v131, v132
	v_max3_f32 v246, v246, v115, v116
	v_max3_f32 v245, v245, v133, v134
	v_max3_f32 v246, v246, v117, v118
	v_max3_f32 v245, v245, v135, v136
	v_max3_f32 v246, v246, v119, v120
	s_waitcnt lgkmcnt(0)
	v_mfma_f32_32x32x16_bf16 v[64:79], v[166:169], v[182:185], v[64:79]
	v_max3_f32 v245, v245, v137, v138
	v_max3_f32 v246, v246, v121, v122
	v_max3_f32 v245, v245, v139, v140
	v_max3_f32 v246, v246, v123, v124
	v_max3_f32 v245, v245, v141, v142
	v_max3_f32 v246, v246, v125, v126
	v_mfma_f32_32x32x16_bf16 v[64:79], v[12:15], v[178:181], v[64:79]
	v_max_f32_e32 v245, v245, v143
	v_max_f32_e32 v246, v246, v127
	v_max_f32_e32 v245, v245, v246
	v_mov_b32_e32 v246, v245
	v_mfma_f32_32x32x16_bf16 v[64:79], v[8:11], v[174:177], v[64:79]
	s_nop 0
	v_permlane32_swap_b32_e32 v245, v246
	v_max_f32_e32 v245, v245, v246
	v_mfma_f32_32x32x16_bf16 v[64:79], v[4:7], v[170:173], v[64:79]
	v_cmp_ge_f32_e32 vcc, s68, v245
	s_cmp_eq_u64 vcc, exec
	v_mov_b32_e32 v225, 1.0
	s_cbranch_scc0 .Lf_odd_resc
.Lf_odd_exp:
	v_exp_f32_e32 v82, v114
	v_exp_f32_e32 v83, v115
	ds_read_b64_tr_b16 v[114:115], v1 offset:0x200
	v_exp_f32_e32 v84, v116
	v_exp_f32_e32 v85, v117
	ds_read_b64_tr_b16 v[116:117], v1 offset:0xa00
	v_exp_f32_e32 v86, v118
	v_exp_f32_e32 v87, v119
	ds_read_b64_tr_b16 v[118:119], v1 offset:0x1200
	v_exp_f32_e32 v88, v120
	v_exp_f32_e32 v89, v121
	ds_read_b64_tr_b16 v[120:121], v1 offset:0x1a00
	v_exp_f32_e32 v90, v122
	v_exp_f32_e32 v91, v123
	ds_read_b64_tr_b16 v[122:123], v1 offset:0x2200
	v_exp_f32_e32 v92, v124
	v_exp_f32_e32 v93, v125
	ds_read_b64_tr_b16 v[124:125], v1 offset:0x2a00
	v_exp_f32_e32 v98, v130
	v_exp_f32_e32 v99, v131
	ds_read_b64_tr_b16 v[130:131], v1 offset:0x3200
	v_exp_f32_e32 v100, v132
	v_exp_f32_e32 v101, v133
	ds_read_b64_tr_b16 v[132:133], v1 offset:0x3a00
	ds_read_b64_tr_b16 v[182:183], v1 offset:0x400
	ds_read_b64_tr_b16 v[184:185], v1 offset:0xc00
	ds_read_b64_tr_b16 v[178:179], v1 offset:0x1400
	ds_read_b64_tr_b16 v[180:181], v1 offset:0x1c00
	ds_read_b64_tr_b16 v[174:175], v1 offset:0x2400
	ds_read_b64_tr_b16 v[176:177], v1 offset:0x2c00
	ds_read_b64_tr_b16 v[170:171], v1 offset:0x3400
	ds_read_b64_tr_b16 v[172:173], v1 offset:0x3c00
	s_waitcnt lgkmcnt(8)
	v_mfma_f32_32x32x16_bf16 v[48:63], v[166:169], v[114:117], v[48:63]
	v_exp_f32_e32 v96, v128
	v_exp_f32_e32 v97, v129
	v_mfma_f32_32x32x16_bf16 v[48:63], v[12:15], v[118:121], v[48:63]
	v_exp_f32_e32 v102, v134
	v_exp_f32_e32 v103, v135
	v_mfma_f32_32x32x16_bf16 v[48:63], v[8:11], v[122:125], v[48:63]
	v_exp_f32_e32 v104, v136
	v_exp_f32_e32 v105, v137
	v_mfma_f32_32x32x16_bf16 v[48:63], v[4:7], v[130:133], v[48:63]
	v_exp_f32_e32 v106, v138
	v_exp_f32_e32 v107, v139
	ds_read_b64_tr_b16 v[114:115], v1 offset:0x600
	ds_read_b64_tr_b16 v[116:117], v1 offset:0xe00
	ds_read_b64_tr_b16 v[118:119], v1 offset:0x1600
	ds_read_b64_tr_b16 v[120:121], v1 offset:0x1e00
	ds_read_b64_tr_b16 v[122:123], v1 offset:0x2600
	ds_read_b64_tr_b16 v[124:125], v1 offset:0x2e00
	ds_read_b64_tr_b16 v[130:131], v1 offset:0x3600
	ds_read_b64_tr_b16 v[132:133], v1 offset:0x3e00
	s_waitcnt lgkmcnt(8)
	v_mfma_f32_32x32x16_bf16 v[32:47], v[166:169], v[182:185], v[32:47]
	v_exp_f32_e32 v108, v140
	v_exp_f32_e32 v109, v141
	v_mfma_f32_32x32x16_bf16 v[32:47], v[12:15], v[178:181], v[32:47]
	v_exp_f32_e32 v110, v142
	v_exp_f32_e32 v111, v143
	v_mfma_f32_32x32x16_bf16 v[32:47], v[8:11], v[174:177], v[32:47]
	v_exp_f32_e32 v80, v112
	v_exp_f32_e32 v81, v113
	v_mfma_f32_32x32x16_bf16 v[32:47], v[4:7], v[170:173], v[32:47]
	v_exp_f32_e32 v94, v126
	v_exp_f32_e32 v95, v127
	s_waitcnt lgkmcnt(0)
	v_mfma_f32_32x32x16_bf16 v[16:31], v[166:169], v[114:117], v[16:31]
	v_mfma_f32_32x32x16_bf16 v[16:31], v[12:15], v[118:121], v[16:31]
	v_mfma_f32_32x32x16_bf16 v[16:31], v[8:11], v[122:125], v[16:31]
	v_mfma_f32_32x32x16_bf16 v[16:31], v[4:7], v[130:133], v[16:31]
	v_cmp_gt_f32_e32 vcc, 1.0, v225
	s_cbranch_vccnz .Lresc_odd_blk
.LBB0_1437:
	s_waitcnt vmcnt(0)
	s_add_i32 s54, s44, 1
	s_cmp_lg_u32 s44, 2
	s_cselect_b32 s67, s54, 0
	s_waitcnt vmcnt(0)
	s_barrier
	s_lshl_b32 s66, s67, 14
	s_add_i32 s54, s81, s66
	v_lshl_add_u64 v[4:5], v[190:191], 0, s[52:53]
	s_mov_b32 m0, s54
	s_add_i32 s52, s71, s82
	global_load_lds_dwordx4 v[4:5], off
	v_lshl_add_u64 v[4:5], v[4:5], 0, s[14:15]
	s_add_i32 m0, s54, 0x2000
	s_add_i32 s52, s52, s27
	global_load_lds_dwordx4 v[4:5], off
	s_add_i32 m0, s52, 0xc000
	s_cmp_ge_u32 s45, s2
	s_cselect_b64 s[52:53], -1, 0
	s_cmp_lt_u32 s45, s2
	s_cselect_b32 s54, s45, s3
	s_lshl_b32 s54, s54, 6
	v_mad_u64_u32 v[4:5], s[54:55], s54, v209, v[192:193]
	v_lshl_add_u64 v[4:5], v[4:5], 0, s[10:11]
	global_load_lds_dwordx4 v[4:5], off
	v_cvt_f32_u32_e32 v1, s65
	s_mul_i32 s54, s44, 0x2100
	s_add_i32 s54, s54, 0
	v_add_u32_e32 v166, s54, v220
	v_sub_f32_e32 v196, v1, v161
	v_add_u32_e32 v167, s54, v217
	v_fma_f32 v1, v210, v196, -v221
	ds_read_b128 v[4:7], v166 offset:49152
	ds_read_b128 v[8:11], v167 offset:49152
	v_cvt_pk_bf16_f32 v2, v1, v3
	v_lshlrev_b32_e32 v2, 16, v2
	v_sub_f32_e32 v1, v1, v2
	v_cvt_pk_bf16_f32 v12, v1, v3
	v_lshlrev_b32_e32 v12, 16, v12
	v_sub_f32_e32 v1, v1, v12
	v_cvt_pk_bf16_f32 v12, v2, v12
	v_cvt_pk_bf16_f32 v1, v1, v3
	s_nop 0
	v_cndmask_b32_e64 v2, 0, v1, s[4:5]
	v_cndmask_b32_e64 v1, 0, v12, s[4:5]
	s_nop 1
	v_mfma_f32_32x32x16_bf16 v[128:143], v[248:251], v[0:3], 0
	s_nop 0
	v_mfma_f32_32x32x16_bf16 v[112:127], v[252:255], v[0:3], 0
	v_add_f32_e32 v1, 0, v96
	v_add_f32_e32 v1, v97, v1
	v_add_f32_e32 v1, v98, v1
	v_add_f32_e32 v1, v99, v1
	v_add_f32_e32 v1, v100, v1
	v_add_f32_e32 v1, v101, v1
	v_add_f32_e32 v1, v102, v1
	s_waitcnt lgkmcnt(0)
	v_mfma_f32_32x32x16_bf16 v[128:143], v[8:11], v[156:159], v[128:143]
	v_add_f32_e32 v1, v103, v1
	v_add_f32_e32 v1, v104, v1
	v_add_f32_e32 v1, v105, v1
	v_add_f32_e32 v1, v106, v1
	v_add_f32_e32 v1, v107, v1
	v_add_f32_e32 v1, v108, v1
	v_add_f32_e32 v1, v109, v1
	v_mfma_f32_32x32x16_bf16 v[112:127], v[4:7], v[156:159], v[112:127]
	ds_read_b128 v[4:7], v166 offset:51264
	ds_read_b128 v[8:11], v167 offset:51264
	v_add_f32_e32 v1, v110, v1
	v_add_f32_e32 v1, v111, v1
	v_add_f32_e32 v1, v80, v1
	v_add_f32_e32 v1, v81, v1
	v_add_f32_e32 v1, v82, v1
	v_add_f32_e32 v1, v83, v1
	s_waitcnt lgkmcnt(0)
	v_mfma_f32_32x32x16_bf16 v[128:143], v[8:11], v[152:155], v[128:143]
	v_add_f32_e32 v1, v84, v1
	v_add_f32_e32 v1, v85, v1
	v_add_f32_e32 v1, v86, v1
	v_add_f32_e32 v1, v87, v1
	v_add_f32_e32 v1, v88, v1
	v_add_f32_e32 v1, v89, v1
	v_add_f32_e32 v1, v90, v1
	v_mfma_f32_32x32x16_bf16 v[112:127], v[4:7], v[152:155], v[112:127]
	ds_read_b128 v[4:7], v166 offset:53376
	ds_read_b128 v[8:11], v167 offset:53376
	v_add_f32_e32 v1, v91, v1
	v_add_f32_e32 v1, v92, v1
	v_add_f32_e32 v1, v93, v1
	v_add_f32_e32 v1, v94, v1
	v_add_f32_e32 v1, v95, v1
	v_mov_b32_e32 v2, v1
	s_waitcnt lgkmcnt(0)
	v_mfma_f32_32x32x16_bf16 v[128:143], v[8:11], v[148:151], v[128:143]
	v_permlane32_swap_b32_e32 v1, v2
	v_mfma_f32_32x32x16_bf16 v[112:127], v[4:7], v[148:151], v[112:127]
	ds_read_b128 v[4:7], v166 offset:55488
	ds_read_b128 v[8:11], v167 offset:55488
	v_cvt_pk_bf16_f32 v166, v96, v97
	v_cvt_pk_bf16_f32 v167, v98, v99
	v_cvt_pk_bf16_f32 v168, v100, v101
	v_cvt_pk_bf16_f32 v169, v102, v103
	v_cvt_pk_bf16_f32 v12, v104, v105
	v_cvt_pk_bf16_f32 v13, v106, v107
	s_waitcnt lgkmcnt(0)
	v_mfma_f32_32x32x16_bf16 v[128:143], v[8:11], v[144:147], v[128:143]
	v_cvt_pk_bf16_f32 v14, v108, v109
	v_cvt_pk_bf16_f32 v15, v110, v111
	v_cvt_pk_bf16_f32 v8, v80, v81
	v_cvt_pk_bf16_f32 v9, v82, v83
	v_cvt_pk_bf16_f32 v10, v84, v85
	v_cvt_pk_bf16_f32 v11, v86, v87
	v_mfma_f32_32x32x16_bf16 v[112:127], v[4:7], v[144:147], v[112:127]
	v_cvt_pk_bf16_f32 v4, v88, v89
	v_cvt_pk_bf16_f32 v5, v90, v91
	v_cvt_pk_bf16_f32 v6, v92, v93
	v_cvt_pk_bf16_f32 v7, v94, v95
	v_lshl_add_u32 v162, s69, 14, v215
	ds_read_b64_tr_b16 v[182:183], v162 offset:0
	ds_read_b64_tr_b16 v[184:185], v162 offset:0x800
	ds_read_b64_tr_b16 v[178:179], v162 offset:0x1000
	ds_read_b64_tr_b16 v[180:181], v162 offset:0x1800
	s_add_i32 s54, s64, s45
	ds_read_b64_tr_b16 v[174:175], v162 offset:0x2000
	s_cmp_eq_u32 s54, 4
	ds_read_b64_tr_b16 v[176:177], v162 offset:0x2800
	s_cselect_b64 s[54:55], -1, 0
	ds_read_b64_tr_b16 v[170:171], v162 offset:0x3000
	v_cndmask_b32_e64 v80, 0, 1, s[54:55]
	ds_read_b64_tr_b16 v[172:173], v162 offset:0x3800
	s_add_i32 s98, s70, 2
	s_cmp_le_i32 s98, s31
	s_cbranch_scc0 .Lold_even
	v_max3_f32 v245, v128, v129, v130
	v_max3_f32 v246, v112, v113, v114
	v_max3_f32 v245, v245, v131, v132
	v_max3_f32 v246, v246, v115, v116
	v_max3_f32 v245, v245, v133, v134
	v_max3_f32 v246, v246, v117, v118
	v_max3_f32 v245, v245, v135, v136
	v_max3_f32 v246, v246, v119, v120
	s_waitcnt lgkmcnt(0)
	v_mfma_f32_32x32x16_bf16 v[64:79], v[166:169], v[182:185], v[64:79]
	v_max3_f32 v245, v245, v137, v138
	v_max3_f32 v246, v246, v121, v122
	v_max3_f32 v245, v245, v139, v140
	v_max3_f32 v246, v246, v123, v124
	v_max3_f32 v245, v245, v141, v142
	v_max3_f32 v246, v246, v125, v126
	v_mfma_f32_32x32x16_bf16 v[64:79], v[12:15], v[178:181], v[64:79]
	v_max_f32_e32 v245, v245, v143
	v_max_f32_e32 v246, v246, v127
	v_max_f32_e32 v245, v245, v246
	v_mov_b32_e32 v246, v245
	v_mfma_f32_32x32x16_bf16 v[64:79], v[8:11], v[174:177], v[64:79]
	s_nop 0
	v_permlane32_swap_b32_e32 v245, v246
	v_max_f32_e32 v245, v245, v246
	v_mfma_f32_32x32x16_bf16 v[64:79], v[4:7], v[170:173], v[64:79]
	v_cmp_ge_f32_e32 vcc, s68, v245
	s_cmp_eq_u64 vcc, exec
	v_mov_b32_e32 v196, 1.0
	s_cbranch_scc0 .Lf_even_resc
.Lf_even_exp:
	v_exp_f32_e32 v82, v114
	v_exp_f32_e32 v83, v115
	ds_read_b64_tr_b16 v[114:115], v162 offset:0x200
	v_exp_f32_e32 v84, v116
	v_exp_f32_e32 v85, v117
	ds_read_b64_tr_b16 v[116:117], v162 offset:0xa00
	v_exp_f32_e32 v86, v118
	v_exp_f32_e32 v87, v119
	ds_read_b64_tr_b16 v[118:119], v162 offset:0x1200
	v_exp_f32_e32 v88, v120
	v_exp_f32_e32 v89, v121
	ds_read_b64_tr_b16 v[120:121], v162 offset:0x1a00
	v_exp_f32_e32 v90, v122
	v_exp_f32_e32 v91, v123
	ds_read_b64_tr_b16 v[122:123], v162 offset:0x2200
	v_exp_f32_e32 v92, v124
	v_exp_f32_e32 v93, v125
	ds_read_b64_tr_b16 v[124:125], v162 offset:0x2a00
	v_exp_f32_e32 v98, v130
	v_exp_f32_e32 v99, v131
	ds_read_b64_tr_b16 v[130:131], v162 offset:0x3200
	v_exp_f32_e32 v100, v132
	v_exp_f32_e32 v101, v133
	ds_read_b64_tr_b16 v[132:133], v162 offset:0x3a00
	ds_read_b64_tr_b16 v[182:183], v162 offset:0x400
	ds_read_b64_tr_b16 v[184:185], v162 offset:0xc00
	ds_read_b64_tr_b16 v[178:179], v162 offset:0x1400
	ds_read_b64_tr_b16 v[180:181], v162 offset:0x1c00
	ds_read_b64_tr_b16 v[174:175], v162 offset:0x2400
	ds_read_b64_tr_b16 v[176:177], v162 offset:0x2c00
	ds_read_b64_tr_b16 v[170:171], v162 offset:0x3400
	ds_read_b64_tr_b16 v[172:173], v162 offset:0x3c00
	s_waitcnt lgkmcnt(8)
	v_mfma_f32_32x32x16_bf16 v[48:63], v[166:169], v[114:117], v[48:63]
	v_exp_f32_e32 v96, v128
	v_exp_f32_e32 v97, v129
	v_mfma_f32_32x32x16_bf16 v[48:63], v[12:15], v[118:121], v[48:63]
	v_exp_f32_e32 v102, v134
	v_exp_f32_e32 v103, v135
	v_mfma_f32_32x32x16_bf16 v[48:63], v[8:11], v[122:125], v[48:63]
	v_exp_f32_e32 v104, v136
	v_exp_f32_e32 v105, v137
	v_mfma_f32_32x32x16_bf16 v[48:63], v[4:7], v[130:133], v[48:63]
	v_exp_f32_e32 v106, v138
	v_exp_f32_e32 v107, v139
	ds_read_b64_tr_b16 v[114:115], v162 offset:0x600
	ds_read_b64_tr_b16 v[116:117], v162 offset:0xe00
	ds_read_b64_tr_b16 v[118:119], v162 offset:0x1600
	ds_read_b64_tr_b16 v[120:121], v162 offset:0x1e00
	ds_read_b64_tr_b16 v[122:123], v162 offset:0x2600
	ds_read_b64_tr_b16 v[124:125], v162 offset:0x2e00
	ds_read_b64_tr_b16 v[130:131], v162 offset:0x3600
	ds_read_b64_tr_b16 v[132:133], v162 offset:0x3e00
	s_waitcnt lgkmcnt(8)
	v_mfma_f32_32x32x16_bf16 v[32:47], v[166:169], v[182:185], v[32:47]
	v_exp_f32_e32 v108, v140
	v_exp_f32_e32 v109, v141
	v_mfma_f32_32x32x16_bf16 v[32:47], v[12:15], v[178:181], v[32:47]
	v_exp_f32_e32 v110, v142
	v_exp_f32_e32 v111, v143
	v_mfma_f32_32x32x16_bf16 v[32:47], v[8:11], v[174:177], v[32:47]
	v_exp_f32_e32 v80, v112
	v_exp_f32_e32 v81, v113
	v_mfma_f32_32x32x16_bf16 v[32:47], v[4:7], v[170:173], v[32:47]
	v_exp_f32_e32 v94, v126
	v_exp_f32_e32 v95, v127
	s_waitcnt lgkmcnt(0)
	v_mfma_f32_32x32x16_bf16 v[16:31], v[166:169], v[114:117], v[16:31]
	v_mfma_f32_32x32x16_bf16 v[16:31], v[12:15], v[118:121], v[16:31]
	v_mfma_f32_32x32x16_bf16 v[16:31], v[8:11], v[122:125], v[16:31]
	v_mfma_f32_32x32x16_bf16 v[16:31], v[4:7], v[130:133], v[16:31]
	v_cmp_gt_f32_e32 vcc, 1.0, v196
	s_cbranch_vccnz .Lresc_even_blk
